# v37_sb
# speedup vs baseline: 1.0237x; 1.0042x over previous
.LBB0_1170:
	s_add_i32 s34, s41, 32
	v_mad_u64_u32 v[136:137], s[44:45], s34, v238, v[130:131]
	global_load_dwordx4 v[66:69], v[136:137], off offset:2048
	global_load_dwordx4 v[114:117], v[136:137], off offset:2080
	global_load_dwordx4 v[118:121], v[136:137], off offset:2112
	global_load_dwordx4 v[198:201], v[136:137], off offset:2144
	global_load_dwordx4 v[202:205], v[136:137], off offset:2176
	global_load_dwordx4 v[206:209], v[136:137], off offset:2208
	global_load_dwordx4 v[210:213], v[136:137], off offset:2240
	global_load_dwordx4 v[214:217], v[136:137], off offset:2272
	v_add_co_u32_e32 v240, vcc, s0, v134
	v_add_f32_e32 v129, 0, v153
	s_cmp_eq_u32 s42, 2
	v_addc_co_u32_e32 v241, vcc, 0, v135, vcc
	global_load_dwordx4 v[218:221], v[134:135], off
	global_load_dwordx4 v[222:225], v[134:135], off offset:16
	s_waitcnt vmcnt(9)
	v_mfma_f32_32x32x16_bf16 v[66:81], v[66:69], v[82:85], 0
	s_waitcnt vmcnt(8)
	v_mfma_f32_32x32x16_bf16 v[66:81], v[114:117], v[86:89], v[66:81]
	s_waitcnt vmcnt(7)
	v_mfma_f32_32x32x16_bf16 v[66:81], v[118:121], v[90:93], v[66:81]
	s_waitcnt vmcnt(6)
	v_mfma_f32_32x32x16_bf16 v[66:81], v[198:201], v[94:97], v[66:81]
	s_waitcnt vmcnt(5)
	v_mfma_f32_32x32x16_bf16 v[66:81], v[202:205], v[98:101], v[66:81]
	s_waitcnt vmcnt(4)
	v_mfma_f32_32x32x16_bf16 v[66:81], v[206:209], v[102:105], v[66:81]
	s_waitcnt vmcnt(3)
	v_mfma_f32_32x32x16_bf16 v[66:81], v[210:213], v[106:109], v[66:81]
	s_waitcnt vmcnt(2)
	v_mfma_f32_32x32x16_bf16 v[66:81], v[214:217], v[110:113], v[66:81]
	global_load_dwordx4 v[198:201], v[134:135], off offset:2048
	global_load_dwordx4 v[202:205], v[134:135], off offset:2064
	global_load_dwordx4 v[206:209], v[240:241], off
	global_load_dwordx4 v[210:213], v[240:241], off offset:16
	global_load_dwordx4 v[214:217], v[240:241], off offset:2048
	global_load_dwordx4 v[226:229], v[240:241], off offset:2064
	s_nop 11
	v_mul_f32_e32 v140, 0x3e0293ee, v66
	v_mul_f32_e32 v144, 0x3e0293ee, v68
	v_mul_f32_e32 v136, 0x3e0293ee, v70
	v_mul_f32_e32 v138, 0x3e0293ee, v71
	v_mul_f32_e32 v146, 0x3e0293ee, v72
	v_mul_f32_e32 v71, 0x3e0293ee, v73
	v_mul_f32_e32 v72, 0x3e0293ee, v74
	v_mul_f32_e32 v74, 0x3e0293ee, v75
	v_mul_f32_e32 v76, 0x3e0293ee, v76
	v_mul_f32_e32 v75, 0x3e0293ee, v77
	v_mul_f32_e32 v66, 0x3e0293ee, v78
	v_mul_f32_e32 v68, 0x3e0293ee, v79
	v_mul_f32_e32 v70, 0x3e0293ee, v80
	v_mul_f32_e32 v79, 0x3e0293ee, v81
	v_mul_f32_e32 v142, 0x3e0293ee, v67
	v_exp_f32_e64 v179, -|v71|
	v_max_f32_e32 v155, 0, v71
	v_exp_f32_e64 v71, -|v72|
	v_exp_f32_e64 v180, -|v74|
	v_exp_f32_e64 v181, -|v76|
	v_exp_f32_e64 v182, -|v75|
	v_max_f32_e32 v159, 0, v75
	v_exp_f32_e64 v75, -|v66|
	v_exp_f32_e64 v183, -|v68|
	v_exp_f32_e64 v184, -|v70|
	v_exp_f32_e64 v185, -|v79|
	v_mul_f32_e32 v67, 0x3e0293ee, v69
	v_exp_f32_e64 v137, -|v140|
	v_exp_f32_e64 v139, -|v142|
	v_exp_f32_e64 v143, -|v144|
	v_exp_f32_e64 v145, -|v67|
	v_exp_f32_e64 v147, -|v136|
	v_exp_f32_e64 v171, -|v138|
	v_exp_f32_e64 v178, -|v146|
	v_add_f32_e32 v71, 1.0, v71
	v_add_f32_e32 v187, 1.0, v180
	v_add_f32_e32 v181, 1.0, v181
	v_add_f32_e32 v189, 1.0, v182
	v_add_f32_e32 v75, 1.0, v75
	v_add_f32_e32 v191, 1.0, v183
	v_add_f32_e32 v192, 1.0, v184
	v_add_f32_e32 v193, 1.0, v185
	v_max_f32_e32 v177, 0, v79
	v_add_f32_e32 v79, 1.0, v137
	v_add_f32_e32 v137, 1.0, v139
	v_log_f32_e32 v186, v71
	v_log_f32_e32 v187, v187
	v_log_f32_e32 v188, v181
	v_log_f32_e32 v189, v189
	v_log_f32_e32 v190, v75
	v_log_f32_e32 v191, v191
	v_log_f32_e32 v192, v192
	v_log_f32_e32 v193, v193
	v_add_f32_e32 v139, 1.0, v143
	v_add_f32_e32 v143, 1.0, v145
	v_add_f32_e32 v145, 1.0, v147
	v_add_f32_e32 v147, 1.0, v171
	v_add_f32_e32 v171, 1.0, v178
	v_log_f32_e32 v178, v79
	v_log_f32_e32 v79, v137
	v_log_f32_e32 v180, v139
	v_max_f32_e32 v156, 0, v72
	v_max_f32_e32 v157, 0, v74
	v_max_f32_e32 v158, 0, v76
	v_max_f32_e32 v160, 0, v66
	v_max_f32_e32 v161, 0, v68
	v_max_f32_e32 v176, 0, v70
	v_add_f32_e32 v179, 1.0, v179
	v_max_f32_e32 v141, 0, v142
	v_log_f32_e32 v137, v143
	v_log_f32_e32 v182, v145
	v_log_f32_e32 v184, v147
	v_log_f32_e32 v183, v171
	v_log_f32_e32 v185, v179
	v_pk_add_f32 v[176:177], v[176:177], v[192:193]
	v_pk_add_f32 v[160:161], v[160:161], v[190:191]
	v_pk_add_f32 v[158:159], v[158:159], v[188:189]
	v_pk_add_f32 v[156:157], v[156:157], v[186:187]
	v_max_f32_e32 v78, 0, v140
	v_max_f32_e32 v80, 0, v144
	v_add_f32_e32 v194, v141, v79
	v_fma_f32 v171, v81, s80, -v177
	v_sub_f32_e64 v181, -v177, v176
	v_sub_f32_e64 v81, -v161, v160
	v_sub_f32_e64 v179, -v159, v158
	v_sub_f32_e64 v79, -v157, v156
	v_pk_add_f32 v[80:81], v[80:81], v[180:181]
	v_pk_add_f32 v[78:79], v[78:79], v[178:179]
	v_max_f32_e32 v67, 0, v67
	v_max_f32_e32 v148, 0, v136
	v_max_f32_e32 v154, 0, v138
	v_max_f32_e32 v149, 0, v146
	v_mov_b32_e32 v139, v81
	v_mov_b32_e32 v141, v81
	v_mov_b32_e32 v143, v79
	v_mov_b32_e32 v145, v79
	v_add_f32_e32 v67, v67, v137
	v_pk_add_f32 v[148:149], v[148:149], v[182:183]
	v_pk_add_f32 v[154:155], v[154:155], v[184:185]
	v_permlane32_swap_b32_e32 v139, v141
	v_permlane32_swap_b32_e32 v143, v145
	v_xor_b32_e32 v182, 0x80000000, v194
	v_xor_b32_e32 v184, 0x80000000, v67
	v_pk_add_f32 v[186:187], v[154:155], v[148:149] neg_lo:[1,1] neg_hi:[1,1]
	v_cndmask_b32_e64 v185, v139, v141, s[8:9]
	v_cndmask_b32_e64 v183, v143, v145, s[8:9]
	v_add_f32_e32 v75, v186, v187
	v_pk_add_f32 v[180:181], v[184:185], v[80:81] neg_lo:[0,1] neg_hi:[0,1]
	v_pk_add_f32 v[186:187], v[184:185], v[80:81]
	v_pk_add_f32 v[190:191], v[182:183], v[78:79] neg_lo:[0,1] neg_hi:[0,1]
	v_pk_add_f32 v[192:193], v[182:183], v[78:79]
	v_fma_f32 v71, v73, s80, -v155
	v_fma_f32 v73, v77, s80, -v159
	v_mov_b32_e32 v77, v75
	v_mov_b32_e32 v137, v75
	v_mov_b32_e32 v181, v187
	v_mov_b32_e32 v191, v193
	v_permlane32_swap_b32_e32 v77, v137
	v_pk_add_f32 v[180:181], v[190:191], v[180:181]
	v_cndmask_b32_e64 v77, v77, v137, s[8:9]
	v_mov_b32_e32 v137, v180
	v_mov_b32_e32 v139, v180
	v_add_f32_e32 v179, v75, v77
	v_cndmask_b32_e64 v75, 0, v77, s[8:9]
	v_add_f32_e32 v141, v153, v181
	v_permlane32_swap_b32_e32 v137, v139
	v_add_f32_e32 v147, v75, v141
	v_cndmask_b32_e64 v178, v137, v139, s[8:9]
	v_add_f32_e32 v71, v71, v147
	v_pk_add_f32 v[180:181], v[180:181], v[178:179]
	v_cndmask_b32_e64 v75, 0, v178, s[8:9]
	v_exp_f32_e32 v178, v71
	v_add_f32_e32 v71, v153, v181
	v_mov_b32_e32 v81, v67
	v_add_f32_e32 v145, v75, v71
	v_fma_f32 v69, v69, s80, -v67
	v_mov_b32_e32 v195, v80
	v_pk_add_f32 v[80:81], v[144:145], v[80:81] neg_lo:[0,1] neg_hi:[0,1]
	v_add_f32_e32 v69, v69, v145
	v_mov_b32_e32 v143, v81
	v_mov_b32_e32 v188, v149
	v_mov_b32_e32 v189, v155
	v_exp_f32_e32 v144, v69
	v_add_f32_e32 v69, v80, v81
	v_pk_add_f32 v[80:81], v[142:143], v[194:195] neg_lo:[0,1] neg_hi:[0,1]
	v_mov_b32_e32 v79, v194
	v_pk_add_f32 v[146:147], v[146:147], v[188:189] neg_lo:[0,1] neg_hi:[0,1]
	v_mov_b32_e32 v141, v81
	v_exp_f32_e32 v145, v69
	v_add_f32_e32 v69, v80, v81
	v_pk_add_f32 v[78:79], v[140:141], v[78:79] neg_lo:[0,1] neg_hi:[0,1]
	v_mov_b32_e32 v139, v147
	v_mov_b32_e32 v155, v149
	v_cndmask_b32_e64 v77, 0, v183, s[8:9]
	v_add_f32_e32 v67, v153, v187
	v_exp_f32_e32 v80, v69
	v_add_f32_e32 v69, v78, v79
	v_pk_add_f32 v[78:79], v[138:139], v[154:155] neg_lo:[0,1] neg_hi:[0,1]
	v_exp_f32_e32 v81, v69
	v_add_f32_e32 v69, v146, v147
	v_mov_b32_e32 v137, v79
	v_mov_b32_e32 v149, v154
	v_add_f32_e32 v77, v77, v67
	v_exp_f32_e32 v140, v69
	v_add_f32_e32 v69, v78, v79
	v_pk_add_f32 v[78:79], v[136:137], v[148:149] neg_lo:[0,1] neg_hi:[0,1]
	v_add_f32_e32 v67, v73, v77
	v_pk_add_f32 v[76:77], v[76:77], v[158:159] neg_lo:[0,1] neg_hi:[0,1]
	v_exp_f32_e32 v138, v69
	v_add_f32_e32 v69, v78, v79
	v_exp_f32_e32 v79, v67
	v_add_f32_e32 v67, v76, v77
	v_mov_b32_e32 v75, v77
	v_pk_mov_b32 v[76:77], v[156:157], v[158:159] op_sel:[1,0]
	v_exp_f32_e32 v136, v67
	v_pk_add_f32 v[74:75], v[74:75], v[76:77] neg_lo:[0,1] neg_hi:[0,1]
	v_exp_f32_e32 v78, v69
	v_mov_b32_e32 v73, v75
	v_add_f32_e32 v67, v74, v75
	v_pk_add_f32 v[72:73], v[72:73], v[156:157] neg_lo:[0,1] neg_hi:[0,1]
	v_exp_f32_e32 v76, v67
	v_add_f32_e32 v67, v72, v73
	v_exp_f32_e32 v77, v67
	v_cndmask_b32_e64 v67, 0, v185, s[8:9]
	v_add_f32_e32 v71, v129, v67
	v_add_f32_e32 v67, v171, v71
	v_pk_add_f32 v[70:71], v[70:71], v[176:177] neg_lo:[0,1] neg_hi:[0,1]
	v_exp_f32_e32 v129, v67
	v_add_f32_e32 v137, v70, v71
	v_mov_b32_e32 v69, v71
	v_pk_mov_b32 v[70:71], v[160:161], v[176:177] op_sel:[1,0]
	s_nop 0
	v_pk_add_f32 v[68:69], v[68:69], v[70:71] neg_lo:[0,1] neg_hi:[0,1]
	v_add_f32_e32 v67, v68, v69
	v_exp_f32_e32 v139, v67
	v_mov_b32_e32 v67, v69
	v_pk_add_f32 v[74:75], v[66:67], v[160:161] neg_lo:[0,1] neg_hi:[0,1]
	v_cvt_pk_bf16_f32 v66, v81, v80
	v_add_f32_e32 v74, v74, v75
	v_cvt_pk_bf16_f32 v68, v78, v138
	v_exp_f32_e32 v78, v74
	v_exp_f32_e32 v80, v137
	v_cvt_pk_bf16_f32 v74, v77, v76
	v_cvt_pk_bf16_f32 v75, v136, v79
	v_cvt_pk_bf16_f32 v76, v78, v139
	v_cvt_pk_bf16_f32 v77, v80, v129
	v_cvt_pk_bf16_f32 v67, v145, v144
	v_cvt_pk_bf16_f32 v69, v140, v178
	s_waitcnt vmcnt(7)
	s_nop 0
	v_mfma_f32_32x32x16_bf16 v[2:17], v[218:221], v[66:69], v[2:17]
	s_waitcnt vmcnt(6)
	v_mfma_f32_32x32x16_bf16 v[2:17], v[222:225], v[74:77], v[2:17]
	s_waitcnt vmcnt(5)
	v_mfma_f32_32x32x16_bf16 v[50:65], v[198:201], v[66:69], v[50:65]
	s_waitcnt vmcnt(4)
	v_mfma_f32_32x32x16_bf16 v[50:65], v[202:205], v[74:77], v[50:65]
	s_waitcnt vmcnt(3)
	v_mfma_f32_32x32x16_bf16 v[34:49], v[206:209], v[66:69], v[34:49]
	s_waitcnt vmcnt(2)
	v_mfma_f32_32x32x16_bf16 v[34:49], v[210:213], v[74:77], v[34:49]
	s_waitcnt vmcnt(1)
	v_mfma_f32_32x32x16_bf16 v[18:33], v[214:217], v[66:69], v[18:33]
	v_add_f32_e32 v66, v180, v181
	v_add_f32_e32 v153, v153, v66
	s_waitcnt vmcnt(0)
	v_mfma_f32_32x32x16_bf16 v[18:33], v[226:229], v[74:77], v[18:33]
	s_cbranch_scc1 .LBB0_1169
	v_mad_u64_u32 v[136:137], s[44:45], s41, v238, v[130:131]
	global_load_dwordx4 v[66:69], v[136:137], off offset:2048
	global_load_dwordx4 v[114:117], v[136:137], off offset:2080
	global_load_dwordx4 v[118:121], v[136:137], off offset:2112
	global_load_dwordx4 v[198:201], v[136:137], off offset:2144
	global_load_dwordx4 v[202:205], v[136:137], off offset:2176
	global_load_dwordx4 v[206:209], v[136:137], off offset:2208
	global_load_dwordx4 v[210:213], v[136:137], off offset:2240
	global_load_dwordx4 v[214:217], v[136:137], off offset:2272
	s_add_i32 s34, s42, -3
	s_lshl_b64 s[44:45], s[34:35], 16
	v_add_f32_e32 v129, 0, v153
	v_lshl_add_u64 v[242:243], v[132:133], 0, s[44:45]
	s_nop 0
	v_add_co_u32_e32 v240, vcc, 0x1000, v242
	s_nop 1
	v_addc_co_u32_e32 v241, vcc, 0, v243, vcc
	global_load_dwordx4 v[218:221], v[242:243], off
	global_load_dwordx4 v[222:225], v[242:243], off offset:16
	s_waitcnt vmcnt(9)
	v_mfma_f32_32x32x16_bf16 v[66:81], v[66:69], v[82:85], 0
	s_waitcnt vmcnt(8)
	v_mfma_f32_32x32x16_bf16 v[66:81], v[114:117], v[86:89], v[66:81]
	s_waitcnt vmcnt(7)
	v_mfma_f32_32x32x16_bf16 v[66:81], v[118:121], v[90:93], v[66:81]
	s_waitcnt vmcnt(6)
	v_mfma_f32_32x32x16_bf16 v[66:81], v[198:201], v[94:97], v[66:81]
	s_waitcnt vmcnt(5)
	v_mfma_f32_32x32x16_bf16 v[66:81], v[202:205], v[98:101], v[66:81]
	s_waitcnt vmcnt(4)
	v_mfma_f32_32x32x16_bf16 v[66:81], v[206:209], v[102:105], v[66:81]
	s_waitcnt vmcnt(3)
	v_mfma_f32_32x32x16_bf16 v[66:81], v[210:213], v[106:109], v[66:81]
	s_waitcnt vmcnt(2)
	v_mfma_f32_32x32x16_bf16 v[66:81], v[214:217], v[110:113], v[66:81]
	global_load_dwordx4 v[198:201], v[242:243], off offset:2048
	global_load_dwordx4 v[202:205], v[242:243], off offset:2064
	global_load_dwordx4 v[206:209], v[240:241], off
	global_load_dwordx4 v[210:213], v[240:241], off offset:16
	global_load_dwordx4 v[214:217], v[240:241], off offset:2048
	global_load_dwordx4 v[226:229], v[240:241], off offset:2064
	s_nop 11
	v_mul_f32_e32 v138, 0x3e0293ee, v66
	v_mul_f32_e32 v142, 0x3e0293ee, v68
	v_mul_f32_e32 v144, 0x3e0293ee, v70
	v_mul_f32_e32 v146, 0x3e0293ee, v71
	v_mul_f32_e32 v148, 0x3e0293ee, v72
	v_mul_f32_e32 v71, 0x3e0293ee, v73
	v_mul_f32_e32 v72, 0x3e0293ee, v74
	v_mul_f32_e32 v74, 0x3e0293ee, v75
	v_mul_f32_e32 v76, 0x3e0293ee, v76
	v_mul_f32_e32 v75, 0x3e0293ee, v77
	v_mul_f32_e32 v66, 0x3e0293ee, v78
	v_mul_f32_e32 v68, 0x3e0293ee, v79
	v_mul_f32_e32 v70, 0x3e0293ee, v80
	v_mul_f32_e32 v79, 0x3e0293ee, v81
	v_mul_f32_e32 v140, 0x3e0293ee, v67
	v_exp_f32_e64 v181, -|v71|
	v_max_f32_e32 v157, 0, v71
	v_exp_f32_e64 v71, -|v72|
	v_exp_f32_e64 v182, -|v74|
	v_exp_f32_e64 v183, -|v76|
	v_exp_f32_e64 v184, -|v75|
	v_max_f32_e32 v161, 0, v75
	v_exp_f32_e64 v75, -|v66|
	v_exp_f32_e64 v185, -|v68|
	v_exp_f32_e64 v186, -|v70|
	v_exp_f32_e64 v187, -|v79|
	v_mul_f32_e32 v67, 0x3e0293ee, v69
	v_exp_f32_e64 v139, -|v138|
	v_exp_f32_e64 v141, -|v140|
	v_exp_f32_e64 v145, -|v142|
	v_exp_f32_e64 v147, -|v67|
	v_exp_f32_e64 v149, -|v144|
	v_exp_f32_e64 v171, -|v146|
	v_exp_f32_e64 v180, -|v148|
	v_add_f32_e32 v71, 1.0, v71
	v_add_f32_e32 v189, 1.0, v182
	v_add_f32_e32 v183, 1.0, v183
	v_add_f32_e32 v191, 1.0, v184
	v_add_f32_e32 v75, 1.0, v75
	v_add_f32_e32 v193, 1.0, v185
	v_add_f32_e32 v194, 1.0, v186
	v_add_f32_e32 v195, 1.0, v187
	v_max_f32_e32 v179, 0, v79
	v_add_f32_e32 v79, 1.0, v139
	v_add_f32_e32 v139, 1.0, v141
	v_log_f32_e32 v188, v71
	v_log_f32_e32 v189, v189
	v_log_f32_e32 v190, v183
	v_log_f32_e32 v191, v191
	v_log_f32_e32 v192, v75
	v_log_f32_e32 v193, v193
	v_log_f32_e32 v194, v194
	v_log_f32_e32 v195, v195
	v_add_f32_e32 v141, 1.0, v145
	v_add_f32_e32 v145, 1.0, v147
	v_add_f32_e32 v147, 1.0, v149
	v_add_f32_e32 v149, 1.0, v171
	v_add_f32_e32 v171, 1.0, v180
	v_log_f32_e32 v180, v79
	v_log_f32_e32 v79, v139
	v_log_f32_e32 v182, v141
	v_max_f32_e32 v158, 0, v72
	v_max_f32_e32 v159, 0, v74
	v_max_f32_e32 v160, 0, v76
	v_max_f32_e32 v176, 0, v66
	v_max_f32_e32 v177, 0, v68
	v_max_f32_e32 v178, 0, v70
	v_add_f32_e32 v181, 1.0, v181
	v_max_f32_e32 v143, 0, v140
	v_log_f32_e32 v139, v145
	v_log_f32_e32 v184, v147
	v_log_f32_e32 v186, v149
	v_log_f32_e32 v185, v171
	v_log_f32_e32 v187, v181
	v_pk_add_f32 v[178:179], v[178:179], v[194:195]
	v_pk_add_f32 v[176:177], v[176:177], v[192:193]
	v_pk_add_f32 v[160:161], v[160:161], v[190:191]
	v_pk_add_f32 v[158:159], v[158:159], v[188:189]
	v_max_f32_e32 v78, 0, v138
	v_max_f32_e32 v80, 0, v142
	v_add_f32_e32 v196, v143, v79
	v_fma_f32 v171, v81, s80, -v179
	v_sub_f32_e64 v183, -v179, v178
	v_sub_f32_e64 v81, -v177, v176
	v_sub_f32_e64 v181, -v161, v160
	v_sub_f32_e64 v79, -v159, v158
	v_pk_add_f32 v[80:81], v[80:81], v[182:183]
	v_pk_add_f32 v[78:79], v[78:79], v[180:181]
	v_max_f32_e32 v67, 0, v67
	v_max_f32_e32 v154, 0, v144
	v_max_f32_e32 v156, 0, v146
	v_max_f32_e32 v155, 0, v148
	v_mov_b32_e32 v141, v81
	v_mov_b32_e32 v143, v81
	v_mov_b32_e32 v145, v79
	v_mov_b32_e32 v147, v79
	v_add_f32_e32 v67, v67, v139
	v_pk_add_f32 v[154:155], v[154:155], v[184:185]
	v_pk_add_f32 v[156:157], v[156:157], v[186:187]
	v_permlane32_swap_b32_e32 v141, v143
	v_permlane32_swap_b32_e32 v145, v147
	v_xor_b32_e32 v184, 0x80000000, v196
	v_xor_b32_e32 v186, 0x80000000, v67
	v_pk_add_f32 v[188:189], v[156:157], v[154:155] neg_lo:[1,1] neg_hi:[1,1]
	v_cndmask_b32_e64 v187, v141, v143, s[8:9]
	v_cndmask_b32_e64 v185, v145, v147, s[8:9]
	v_add_f32_e32 v75, v188, v189
	v_pk_add_f32 v[182:183], v[186:187], v[80:81] neg_lo:[0,1] neg_hi:[0,1]
	v_pk_add_f32 v[188:189], v[186:187], v[80:81]
	v_pk_add_f32 v[190:191], v[184:185], v[78:79] neg_lo:[0,1] neg_hi:[0,1]
	v_pk_add_f32 v[192:193], v[184:185], v[78:79]
	v_fma_f32 v71, v73, s80, -v157
	v_fma_f32 v73, v77, s80, -v161
	v_mov_b32_e32 v77, v75
	v_mov_b32_e32 v139, v75
	v_mov_b32_e32 v183, v189
	v_mov_b32_e32 v191, v193
	v_permlane32_swap_b32_e32 v77, v139
	v_pk_add_f32 v[182:183], v[190:191], v[182:183]
	v_cndmask_b32_e64 v77, v77, v139, s[8:9]
	v_mov_b32_e32 v139, v182
	v_mov_b32_e32 v141, v182
	v_add_f32_e32 v181, v75, v77
	v_cndmask_b32_e64 v75, 0, v77, s[8:9]
	v_add_f32_e32 v143, v153, v183
	v_permlane32_swap_b32_e32 v139, v141
	v_add_f32_e32 v149, v75, v143
	v_cndmask_b32_e64 v180, v139, v141, s[8:9]
	v_add_f32_e32 v71, v71, v149
	v_pk_add_f32 v[182:183], v[182:183], v[180:181]
	v_cndmask_b32_e64 v75, 0, v180, s[8:9]
	v_exp_f32_e32 v180, v71
	v_add_f32_e32 v71, v153, v183
	v_mov_b32_e32 v81, v67
	v_add_f32_e32 v143, v75, v71
	v_fma_f32 v69, v69, s80, -v67
	v_mov_b32_e32 v197, v80
	v_pk_add_f32 v[80:81], v[142:143], v[80:81] neg_lo:[0,1] neg_hi:[0,1]
	v_add_f32_e32 v69, v69, v143
	v_mov_b32_e32 v141, v81
	v_exp_f32_e32 v142, v69
	v_add_f32_e32 v69, v80, v81
	v_pk_add_f32 v[80:81], v[140:141], v[196:197] neg_lo:[0,1] neg_hi:[0,1]
	v_mov_b32_e32 v79, v196
	v_mov_b32_e32 v139, v81
	v_exp_f32_e32 v143, v69
	v_add_f32_e32 v69, v80, v81
	v_pk_add_f32 v[78:79], v[138:139], v[78:79] neg_lo:[0,1] neg_hi:[0,1]
	v_exp_f32_e32 v80, v69
	v_add_f32_e32 v69, v78, v79
	v_mov_b32_e32 v78, v155
	v_mov_b32_e32 v79, v157
	v_pk_add_f32 v[78:79], v[148:149], v[78:79] neg_lo:[0,1] neg_hi:[0,1]
	v_mov_b32_e32 v157, v155
	v_mov_b32_e32 v147, v79
	v_cndmask_b32_e64 v77, 0, v185, s[8:9]
	v_add_f32_e32 v67, v153, v189
	v_exp_f32_e32 v81, v69
	v_add_f32_e32 v69, v78, v79
	v_pk_add_f32 v[78:79], v[146:147], v[156:157] neg_lo:[0,1] neg_hi:[0,1]
	v_mov_b32_e32 v155, v156
	v_mov_b32_e32 v145, v79
	v_add_f32_e32 v77, v77, v67
	v_exp_f32_e32 v138, v69
	v_add_f32_e32 v69, v78, v79
	v_pk_add_f32 v[78:79], v[144:145], v[154:155] neg_lo:[0,1] neg_hi:[0,1]
	v_add_f32_e32 v67, v73, v77
	v_pk_add_f32 v[76:77], v[76:77], v[160:161] neg_lo:[0,1] neg_hi:[0,1]
	v_exp_f32_e32 v139, v69
	v_add_f32_e32 v69, v78, v79
	v_exp_f32_e32 v79, v67
	v_add_f32_e32 v67, v76, v77
	v_mov_b32_e32 v75, v77
	v_pk_mov_b32 v[76:77], v[158:159], v[160:161] op_sel:[1,0]
	v_exp_f32_e32 v140, v67
	v_pk_add_f32 v[74:75], v[74:75], v[76:77] neg_lo:[0,1] neg_hi:[0,1]
	v_exp_f32_e32 v78, v69
	v_mov_b32_e32 v73, v75
	v_add_f32_e32 v67, v74, v75
	v_pk_add_f32 v[72:73], v[72:73], v[158:159] neg_lo:[0,1] neg_hi:[0,1]
	v_exp_f32_e32 v76, v67
	v_add_f32_e32 v67, v72, v73
	v_exp_f32_e32 v77, v67
	v_cndmask_b32_e64 v67, 0, v187, s[8:9]
	v_add_f32_e32 v71, v129, v67
	v_add_f32_e32 v67, v171, v71
	v_pk_add_f32 v[70:71], v[70:71], v[178:179] neg_lo:[0,1] neg_hi:[0,1]
	v_exp_f32_e32 v129, v67
	v_add_f32_e32 v141, v70, v71
	v_mov_b32_e32 v69, v71
	v_pk_mov_b32 v[70:71], v[176:177], v[178:179] op_sel:[1,0]
	s_nop 0
	v_pk_add_f32 v[68:69], v[68:69], v[70:71] neg_lo:[0,1] neg_hi:[0,1]
	v_add_f32_e32 v67, v68, v69
	v_exp_f32_e32 v144, v67
	v_mov_b32_e32 v67, v69
	v_pk_add_f32 v[74:75], v[66:67], v[176:177] neg_lo:[0,1] neg_hi:[0,1]
	v_cvt_pk_bf16_f32 v66, v81, v80
	v_add_f32_e32 v74, v74, v75
	v_cvt_pk_bf16_f32 v68, v78, v139
	v_exp_f32_e32 v78, v74
	v_exp_f32_e32 v80, v141
	v_cvt_pk_bf16_f32 v74, v77, v76
	v_cvt_pk_bf16_f32 v75, v140, v79
	v_cvt_pk_bf16_f32 v76, v78, v144
	v_cvt_pk_bf16_f32 v77, v80, v129
	v_cvt_pk_bf16_f32 v67, v143, v142
	v_cvt_pk_bf16_f32 v69, v138, v180
	s_waitcnt vmcnt(7)
	s_nop 0
	v_mfma_f32_32x32x16_bf16 v[2:17], v[218:221], v[66:69], v[2:17]
	s_waitcnt vmcnt(6)
	v_mfma_f32_32x32x16_bf16 v[2:17], v[222:225], v[74:77], v[2:17]
	s_waitcnt vmcnt(5)
	v_mfma_f32_32x32x16_bf16 v[50:65], v[198:201], v[66:69], v[50:65]
	s_waitcnt vmcnt(4)
	v_mfma_f32_32x32x16_bf16 v[50:65], v[202:205], v[74:77], v[50:65]
	s_waitcnt vmcnt(3)
	v_mfma_f32_32x32x16_bf16 v[34:49], v[206:209], v[66:69], v[34:49]
	s_waitcnt vmcnt(2)
	v_mfma_f32_32x32x16_bf16 v[34:49], v[210:213], v[74:77], v[34:49]
	s_waitcnt vmcnt(1)
	v_mfma_f32_32x32x16_bf16 v[18:33], v[214:217], v[66:69], v[18:33]
	v_add_f32_e32 v66, v182, v183
	v_add_f32_e32 v153, v153, v66
	s_waitcnt vmcnt(0)
	v_mfma_f32_32x32x16_bf16 v[18:33], v[226:229], v[74:77], v[18:33]
	s_branch .LBB0_1169
